# hand-written conv_sample_kv: one workgroup per (b,h), 8x16B loads in flight, V^T via LDS transpose with whole-row stores
# speedup vs baseline: 1.0148x; 1.0138x over previous
; __device__ __forceinline__ int tidx() { int t = threadIdx.x; asm volatile("" : "+v"(t)); return t; }
; __device__ __forceinline__ float4 ldnt4(const float* p) { const f32x4 v = __builtin_nontemporal_load((const f32x4*)p); return make_float4(v[0], v[1], v[2], v[3]); }
; __device__ __forceinline__ void conv_sample_kv(KP p, int l) {
;     const int tid_ = tidx();
;     const size_t gt = (size_t)blockIdx.x * 256 + tid_, gs = (size_t)gridDim.x * 256;
;     const float* ck = p->in[I_CMK] + (size_t)l * 128 * 256 * 256;
;     const float* cv = p->in[I_CMV] + (size_t)l * 128 * 256 * 256;
;     bf16_t* Ks = (bf16_t*)(p->ws + OFF_KS); bf16_t* Vts = (bf16_t*)(p->ws + OFF_VTS);
;     for (size_t i0 = gt; i0 < (size_t)128 * 256 * 64; i0 += 4 * gs) {
;         float4 v[4];
; #pragma unroll
;         for (int u = 0; u < 4; ++u) { const size_t i = i0 + u * gs; if (i < (size_t)128 * 256 * 64) v[u] = ldnt4(ck + i * 4); }
; #pragma unroll
;         for (int u = 0; u < 4; ++u) {
;             const size_t i = i0 + u * gs;
;             if (i < (size_t)128 * 256 * 64) {
;                 const int d4 = i & 15, h = (i >> 4) & 3, key = (i >> 6) & 255, b = (int)(i >> 14);
;                 *(uint2*)(Ks + ((size_t)(b * 4 + h) * 256 + key) * 64 + d4 * 4) = make_uint2(pack2(v[u].x, v[u].y), pack2(v[u].z, v[u].w));
;             }
;         }
;     }
.LBB0_489:
	v_readlane_b32 s82, v230, 21
	v_readlane_b32 s83, v230, 22
	v_readlane_b32 s84, v231, 14
	v_readlane_b32 s90, v231, 34
	s_and_b64 vcc, exec, s[14:15]
	v_readlane_b32 s75, v233, 29
	v_readlane_b32 s83, v233, 30
	v_readlane_b32 s85, v231, 15
	v_readlane_b32 s91, v231, 35
	s_movk_i32 s28, 0x7f00
	s_cbranch_vccz .LBB0_1475
	v_readlane_b32 s12, v230, 27
	v_readlane_b32 s13, v230, 28
	s_andn2_b64 vcc, exec, s[12:13]
	s_cbranch_vccnz .LBB0_521
	v_and_b32_e32 v242, 15, v192
	v_lshrrev_b32_e32 v243, 4, v192
	v_lshlrev_b32_e32 v236, 4, v242
	v_lshl_add_u32 v238, v243, 12, v236
	v_lshl_add_u32 v236, v243, 10, v236
	v_lshlrev_b32_e32 v237, 3, v242
	v_lshl_add_u32 v237, v243, 7, v237
	v_mul_u32_u24_e32 v239, 0x840, v242
	v_lshl_add_u32 v239, v243, 3, v239
	v_and_b32_e32 v242, 31, v192
	v_lshrrev_b32_e32 v243, 5, v192
	v_lshlrev_b32_e32 v241, 4, v242
	v_mul_u32_u24_e32 v240, 0x210, v243
	v_add_u32_e32 v240, v240, v241
	v_lshl_add_u32 v241, v243, 9, v241
	s_load_dwordx4 s[44:47], s[16:17], 0x18
	v_readlane_b32 s12, v230, 25
	v_readlane_b32 s24, v231, 56
	s_nop 1
	v_writelane_b32 v230, s12, 25
	v_writelane_b32 v230, s3, 26
	s_ashr_i32 s13, s12, 31
	s_lshl_b64 s[22:23], s[12:13], 25
	s_waitcnt lgkmcnt(0)
	s_add_u32 s44, s44, s22
	s_addc_u32 s45, s45, s23
	s_add_u32 s46, s46, s22
	s_addc_u32 s47, s47, s23
	s_cmpk_lt_u32 s24, 0x200
	s_cbranch_scc0 .Lconv_done
.Lconv_pair:
	s_lshr_b32 s2, s24, 2
	s_lshl_b32 s2, s2, 18
	s_and_b32 s11, s24, 3
	s_lshl_b32 s11, s11, 8
	s_or_b32 s2, s2, s11
	s_add_u32 s40, s44, s2
	s_addc_u32 s41, s45, 0
	s_add_u32 s42, s46, s2
	s_addc_u32 s43, s47, 0
	s_lshl_b32 s2, s24, 15
	s_add_u32 s48, s58, 0x3f20000
	s_addc_u32 s49, s59, 0
	s_add_u32 s48, s48, s2
	s_addc_u32 s49, s49, 0
	s_add_u32 s50, s58, 0x4f20000
	s_addc_u32 s51, s59, 0
	s_add_u32 s50, s50, s2
	s_addc_u32 s51, s51, 0
	s_mov_b64 s[52:53], s[40:41]
	s_mov_b64 s[54:55], s[48:49]
	global_load_dwordx4 v[0:3], v236, s[52:53] nt
	s_add_u32 s52, s52, 0x4000
	s_addc_u32 s53, s53, 0
	global_load_dwordx4 v[4:7], v236, s[52:53] nt
	s_add_u32 s52, s52, 0x4000
	s_addc_u32 s53, s53, 0
	global_load_dwordx4 v[8:11], v236, s[52:53] nt
	s_add_u32 s52, s52, 0x4000
	s_addc_u32 s53, s53, 0
	global_load_dwordx4 v[14:17], v236, s[52:53] nt
	s_add_u32 s52, s52, 0x4000
	s_addc_u32 s53, s53, 0
	global_load_dwordx4 v[18:21], v236, s[52:53] nt
	s_add_u32 s52, s52, 0x4000
	s_addc_u32 s53, s53, 0
	global_load_dwordx4 v[22:25], v236, s[52:53] nt
	s_add_u32 s52, s52, 0x4000
	s_addc_u32 s53, s53, 0
	global_load_dwordx4 v[26:29], v236, s[52:53] nt
	s_add_u32 s52, s52, 0x4000
	s_addc_u32 s53, s53, 0
	global_load_dwordx4 v[30:33], v236, s[52:53] nt
	s_add_u32 s52, s52, 0x4000
	s_addc_u32 s53, s53, 0
	s_waitcnt vmcnt(7)
	v_cvt_pk_bf16_f32 v242, v0, v1
	v_cvt_pk_bf16_f32 v243, v2, v3
	global_store_dwordx2 v237, v[242:243], s[54:55]
	s_add_u32 s54, s54, 0x800
	s_addc_u32 s55, s55, 0
	s_waitcnt vmcnt(7)
	v_cvt_pk_bf16_f32 v244, v4, v5
	v_cvt_pk_bf16_f32 v245, v6, v7
	global_store_dwordx2 v237, v[244:245], s[54:55]
	s_add_u32 s54, s54, 0x800
	s_addc_u32 s55, s55, 0
	s_waitcnt vmcnt(7)
	v_cvt_pk_bf16_f32 v246, v8, v9
	v_cvt_pk_bf16_f32 v247, v10, v11
	global_store_dwordx2 v237, v[246:247], s[54:55]
	s_add_u32 s54, s54, 0x800
	s_addc_u32 s55, s55, 0
	s_waitcnt vmcnt(7)
	v_cvt_pk_bf16_f32 v248, v14, v15
	v_cvt_pk_bf16_f32 v249, v16, v17
	global_store_dwordx2 v237, v[248:249], s[54:55]
	s_add_u32 s54, s54, 0x800
	s_addc_u32 s55, s55, 0
	s_waitcnt vmcnt(7)
	v_cvt_pk_bf16_f32 v242, v18, v19
	v_cvt_pk_bf16_f32 v243, v20, v21
	global_store_dwordx2 v237, v[242:243], s[54:55]
	s_add_u32 s54, s54, 0x800
	s_addc_u32 s55, s55, 0
	s_waitcnt vmcnt(7)
	v_cvt_pk_bf16_f32 v244, v22, v23
	v_cvt_pk_bf16_f32 v245, v24, v25
	global_store_dwordx2 v237, v[244:245], s[54:55]
	s_add_u32 s54, s54, 0x800
	s_addc_u32 s55, s55, 0
	s_waitcnt vmcnt(7)
	v_cvt_pk_bf16_f32 v246, v26, v27
	v_cvt_pk_bf16_f32 v247, v28, v29
	global_store_dwordx2 v237, v[246:247], s[54:55]
	s_add_u32 s54, s54, 0x800
	s_addc_u32 s55, s55, 0
	s_waitcnt vmcnt(7)
	v_cvt_pk_bf16_f32 v248, v30, v31
	v_cvt_pk_bf16_f32 v249, v32, v33
	global_store_dwordx2 v237, v[248:249], s[54:55]
	s_add_u32 s54, s54, 0x800
	s_addc_u32 s55, s55, 0
	global_load_dwordx4 v[0:3], v236, s[52:53] nt
	s_add_u32 s52, s52, 0x4000
	s_addc_u32 s53, s53, 0
	global_load_dwordx4 v[4:7], v236, s[52:53] nt
	s_add_u32 s52, s52, 0x4000
	s_addc_u32 s53, s53, 0
	global_load_dwordx4 v[8:11], v236, s[52:53] nt
	s_add_u32 s52, s52, 0x4000
	s_addc_u32 s53, s53, 0
	global_load_dwordx4 v[14:17], v236, s[52:53] nt
	s_add_u32 s52, s52, 0x4000
	s_addc_u32 s53, s53, 0
	global_load_dwordx4 v[18:21], v236, s[52:53] nt
	s_add_u32 s52, s52, 0x4000
	s_addc_u32 s53, s53, 0
	global_load_dwordx4 v[22:25], v236, s[52:53] nt
	s_add_u32 s52, s52, 0x4000
	s_addc_u32 s53, s53, 0
	global_load_dwordx4 v[26:29], v236, s[52:53] nt
	s_add_u32 s52, s52, 0x4000
	s_addc_u32 s53, s53, 0
	global_load_dwordx4 v[30:33], v236, s[52:53] nt
	s_add_u32 s52, s52, 0x4000
	s_addc_u32 s53, s53, 0
	s_waitcnt vmcnt(7)
	v_cvt_pk_bf16_f32 v242, v0, v1
	v_cvt_pk_bf16_f32 v243, v2, v3
	global_store_dwordx2 v237, v[242:243], s[54:55]
	s_add_u32 s54, s54, 0x800
	s_addc_u32 s55, s55, 0
	s_waitcnt vmcnt(7)
	v_cvt_pk_bf16_f32 v244, v4, v5
	v_cvt_pk_bf16_f32 v245, v6, v7
	global_store_dwordx2 v237, v[244:245], s[54:55]
	s_add_u32 s54, s54, 0x800
	s_addc_u32 s55, s55, 0
	s_waitcnt vmcnt(7)
	v_cvt_pk_bf16_f32 v246, v8, v9
	v_cvt_pk_bf16_f32 v247, v10, v11
	global_store_dwordx2 v237, v[246:247], s[54:55]
	s_add_u32 s54, s54, 0x800
	s_addc_u32 s55, s55, 0
	s_waitcnt vmcnt(7)
; __device__ __forceinline__ float ldnt(const float* p) { return __builtin_nontemporal_load(p); }
; __device__ __forceinline__ void conv_sample_kv(KP p, int l) {
;     ...
;     for (size_t i0 = gt; i0 < (size_t)128 * 64 * 256; i0 += 4 * gs) {
;         float v[4][4];
; #pragma unroll
;         for (int u = 0; u < 4; ++u) {
;             const size_t i = i0 + u * gs;
;             if (i < (size_t)128 * 64 * 256) {
;                 const int d = i & 63, h = (i >> 6) & 3, kq = (i >> 8) & 63, b = (int)(i >> 14);
; #pragma unroll
;                 for (int j = 0; j < 4; ++j) v[u][j] = ldnt(cv + ((size_t)(b * 256 + kq * 4 + j) * 4 + h) * 64 + d);
;             }
;         }
; #pragma unroll
;         for (int u = 0; u < 4; ++u) {
;             const size_t i = i0 + u * gs;
;             if (i < (size_t)128 * 64 * 256) {
;                 const int d = i & 63, h = (i >> 6) & 3, kq = (i >> 8) & 63, b = (int)(i >> 14);
;                 *(uint2*)(Vts + ((size_t)(b * 4 + h) * 64 + d) * 256 + kq * 4) = make_uint2(pack2(v[u][0], v[u][1]), pack2(v[u][2], v[u][3]));
;             }
;         }
;     }
	v_cvt_pk_bf16_f32 v248, v14, v15
	v_cvt_pk_bf16_f32 v249, v16, v17
	global_store_dwordx2 v237, v[248:249], s[54:55]
	s_add_u32 s54, s54, 0x800
	s_addc_u32 s55, s55, 0
	s_waitcnt vmcnt(7)
	v_cvt_pk_bf16_f32 v242, v18, v19
	v_cvt_pk_bf16_f32 v243, v20, v21
	global_store_dwordx2 v237, v[242:243], s[54:55]
	s_add_u32 s54, s54, 0x800
	s_addc_u32 s55, s55, 0
	s_waitcnt vmcnt(7)
	v_cvt_pk_bf16_f32 v244, v22, v23
	v_cvt_pk_bf16_f32 v245, v24, v25
	global_store_dwordx2 v237, v[244:245], s[54:55]
	s_add_u32 s54, s54, 0x800
	s_addc_u32 s55, s55, 0
	s_waitcnt vmcnt(7)
	v_cvt_pk_bf16_f32 v246, v26, v27
	v_cvt_pk_bf16_f32 v247, v28, v29
	global_store_dwordx2 v237, v[246:247], s[54:55]
	s_add_u32 s54, s54, 0x800
	s_addc_u32 s55, s55, 0
	s_waitcnt vmcnt(7)
	v_cvt_pk_bf16_f32 v248, v30, v31
	v_cvt_pk_bf16_f32 v249, v32, v33
	global_store_dwordx2 v237, v[248:249], s[54:55]
	s_add_u32 s54, s54, 0x800
	s_addc_u32 s55, s55, 0
	s_mov_b64 s[52:53], s[42:43]
	global_load_dwordx4 v[0:3], v238, s[52:53] nt
	global_load_dwordx4 v[4:7], v238, s[52:53] offset:1024 nt
	global_load_dwordx4 v[8:11], v238, s[52:53] offset:2048 nt
	global_load_dwordx4 v[14:17], v238, s[52:53] offset:3072 nt
	s_add_u32 s52, s52, 0x10000
	s_addc_u32 s53, s53, 0
	global_load_dwordx4 v[18:21], v238, s[52:53] nt
	global_load_dwordx4 v[22:25], v238, s[52:53] offset:1024 nt
	global_load_dwordx4 v[26:29], v238, s[52:53] offset:2048 nt
	global_load_dwordx4 v[30:33], v238, s[52:53] offset:3072 nt
	s_add_u32 s52, s52, 0x10000
	s_addc_u32 s53, s53, 0
	s_waitcnt vmcnt(4)
	v_cvt_pk_bf16_f32 v242, v0, v4
	v_cvt_pk_bf16_f32 v243, v8, v14
	v_cvt_pk_bf16_f32 v244, v1, v5
	v_cvt_pk_bf16_f32 v245, v9, v15
	v_cvt_pk_bf16_f32 v246, v2, v6
	v_cvt_pk_bf16_f32 v247, v10, v16
	v_cvt_pk_bf16_f32 v248, v3, v7
	v_cvt_pk_bf16_f32 v249, v11, v17
	ds_write_b64 v239, v[242:243] offset:0
	ds_write_b64 v239, v[244:245] offset:528
	ds_write_b64 v239, v[246:247] offset:1056
	ds_write_b64 v239, v[248:249] offset:1584
	s_waitcnt vmcnt(0)
	v_cvt_pk_bf16_f32 v242, v18, v22
	v_cvt_pk_bf16_f32 v243, v26, v30
	v_cvt_pk_bf16_f32 v244, v19, v23
	v_cvt_pk_bf16_f32 v245, v27, v31
	v_cvt_pk_bf16_f32 v246, v20, v24
	v_cvt_pk_bf16_f32 v247, v28, v32
	v_cvt_pk_bf16_f32 v248, v21, v25
	v_cvt_pk_bf16_f32 v249, v29, v33
	ds_write_b64 v239, v[242:243] offset:128
	ds_write_b64 v239, v[244:245] offset:656
	ds_write_b64 v239, v[246:247] offset:1184
	ds_write_b64 v239, v[248:249] offset:1712
	global_load_dwordx4 v[0:3], v238, s[52:53] nt
	global_load_dwordx4 v[4:7], v238, s[52:53] offset:1024 nt
	global_load_dwordx4 v[8:11], v238, s[52:53] offset:2048 nt
	global_load_dwordx4 v[14:17], v238, s[52:53] offset:3072 nt
	s_add_u32 s52, s52, 0x10000
	s_addc_u32 s53, s53, 0
	global_load_dwordx4 v[18:21], v238, s[52:53] nt
	global_load_dwordx4 v[22:25], v238, s[52:53] offset:1024 nt
	global_load_dwordx4 v[26:29], v238, s[52:53] offset:2048 nt
	global_load_dwordx4 v[30:33], v238, s[52:53] offset:3072 nt
	s_add_u32 s52, s52, 0x10000
	s_addc_u32 s53, s53, 0
	s_waitcnt vmcnt(4)
	v_cvt_pk_bf16_f32 v242, v0, v4
	v_cvt_pk_bf16_f32 v243, v8, v14
	v_cvt_pk_bf16_f32 v244, v1, v5
	v_cvt_pk_bf16_f32 v245, v9, v15
	v_cvt_pk_bf16_f32 v246, v2, v6
	v_cvt_pk_bf16_f32 v247, v10, v16
	v_cvt_pk_bf16_f32 v248, v3, v7
	v_cvt_pk_bf16_f32 v249, v11, v17
	ds_write_b64 v239, v[242:243] offset:256
	ds_write_b64 v239, v[244:245] offset:784
	ds_write_b64 v239, v[246:247] offset:1312
	ds_write_b64 v239, v[248:249] offset:1840
	s_waitcnt vmcnt(0)
	v_cvt_pk_bf16_f32 v242, v18, v22
	v_cvt_pk_bf16_f32 v243, v26, v30
	v_cvt_pk_bf16_f32 v244, v19, v23
	v_cvt_pk_bf16_f32 v245, v27, v31
	v_cvt_pk_bf16_f32 v246, v20, v24
	v_cvt_pk_bf16_f32 v247, v28, v32
	v_cvt_pk_bf16_f32 v248, v21, v25
	v_cvt_pk_bf16_f32 v249, v29, v33
	ds_write_b64 v239, v[242:243] offset:384
	ds_write_b64 v239, v[244:245] offset:912
	ds_write_b64 v239, v[246:247] offset:1440
	ds_write_b64 v239, v[248:249] offset:1968
	s_waitcnt lgkmcnt(0)
	s_barrier
	s_mov_b64 s[54:55], s[50:51]
	ds_read_b128 v[244:247], v240 offset:0
	s_waitcnt lgkmcnt(0)
	global_store_dwordx4 v241, v[244:247], s[54:55]
	s_add_u32 s54, s54, 0x1000
	s_addc_u32 s55, s55, 0
	ds_read_b128 v[248:251], v240 offset:4224
	s_waitcnt lgkmcnt(0)
	global_store_dwordx4 v241, v[248:251], s[54:55]
	s_add_u32 s54, s54, 0x1000
	s_addc_u32 s55, s55, 0
	ds_read_b128 v[244:247], v240 offset:8448
	s_waitcnt lgkmcnt(0)
	global_store_dwordx4 v241, v[244:247], s[54:55]
	s_add_u32 s54, s54, 0x1000
	s_addc_u32 s55, s55, 0
	ds_read_b128 v[248:251], v240 offset:12672
	s_waitcnt lgkmcnt(0)
	global_store_dwordx4 v241, v[248:251], s[54:55]
	s_add_u32 s54, s54, 0x1000
	s_addc_u32 s55, s55, 0
	ds_read_b128 v[244:247], v240 offset:16896
	s_waitcnt lgkmcnt(0)
	global_store_dwordx4 v241, v[244:247], s[54:55]
	s_add_u32 s54, s54, 0x1000
	s_addc_u32 s55, s55, 0
	ds_read_b128 v[248:251], v240 offset:21120
	s_waitcnt lgkmcnt(0)
	global_store_dwordx4 v241, v[248:251], s[54:55]
	s_add_u32 s54, s54, 0x1000
	s_addc_u32 s55, s55, 0
	ds_read_b128 v[244:247], v240 offset:25344
	s_waitcnt lgkmcnt(0)
	global_store_dwordx4 v241, v[244:247], s[54:55]
	s_add_u32 s54, s54, 0x1000
	s_addc_u32 s55, s55, 0
	ds_read_b128 v[248:251], v240 offset:29568
	s_waitcnt lgkmcnt(0)
	global_store_dwordx4 v241, v[248:251], s[54:55]
	s_add_u32 s54, s54, 0x1000
	s_addc_u32 s55, s55, 0
	s_barrier
	s_add_i32 s24, s24, s62
	s_cmpk_lt_u32 s24, 0x200
	s_cbranch_scc1 .Lconv_pair
.Lconv_done:
.LBB0_521:
	v_readlane_b32 s12, v230, 23
	v_readlane_b32 s13, v230, 24
	s_xor_b64 s[12:13], s[12:13], -1
	s_and_b64 vcc, exec, s[12:13]
	s_cbranch_vccz .LBB0_523
	s_cmp_eq_u32 s10, 12
	s_cselect_b64 s[12:13], -1, 0
	s_cmp_lt_i32 s82, 40
	s_cselect_b64 s[14:15], -1, 0
	s_and_b64 s[14:15], s[14:15], s[12:13]
	s_mov_b64 s[12:13], 0
	s_branch .LBB0_524
